# instruction selection: FF1 SwiGLU epilogue regenerated with packed f32 VALU ops (v_pk_fma/v_pk_mul, in place on the accumulators), bit-identical math
# speedup vs baseline: 1.0015x; 1.0015x over previous
; __device__ __forceinline__ u32x4 pack8(const f32x4 v0, const f32x4 v1) { u32x4 w; w.x = cvt_pk_bf16(v0[0], v0[1]); w.y = cvt_pk_bf16(v0[2], v0[3]); w.z = cvt_pk_bf16(v1[0], v1[1]); w.w = cvt_pk_bf16(v1[2], v1[3]); return w; }
;     __device__ __forceinline__ void operator()(const f32x4 (&acc)[2][2][4][2], const Unit& u, int wr, int wc, int fr, int fq) const {
;         const int row0 = u.pm * BM + wr * 64 + fr, col0 = u.pn * BM + wc * 32 + 8 * fq;
;         float mu[2][4], rs[2][4]; row_stats8(MUR, row0, mu, rs);
;         if (u.pn >= 4) {
;     ...
;             const int ucol = u.pn * HALF + wc * 32 + 8 * fq;
;             const f32x4 sa0 = *(const f32x4*)(cs + col0), sa1 = *(const f32x4*)(cs + col0 + 4), ba0 = *(const f32x4*)(cb + col0), ba1 = *(const f32x4*)(cb + col0 + 4);
;             const f32x4 sg0 = *(const f32x4*)(cs + col0 + HALF), sg1 = *(const f32x4*)(cs + col0 + HALF + 4), bg0 = *(const f32x4*)(cb + col0 + HALF), bg1 = *(const f32x4*)(cb + col0 + HALF + 4);
; #pragma unroll
;             for (int ai = 0; ai < 2; ++ai)
; #pragma unroll
;                 for (int m = 0; m < 4; ++m) {
;                     const f32x4 a0 = (acc[ai][0][m][0] - sa0 * mu[ai][m]) * rs[ai][m] + ba0, a1 = (acc[ai][0][m][1] - sa1 * mu[ai][m]) * rs[ai][m] + ba1;
;                     const f32x4 g0 = (acc[ai][1][m][0] - sg0 * mu[ai][m]) * rs[ai][m] + bg0, g1 = (acc[ai][1][m][1] - sg1 * mu[ai][m]) * rs[ai][m] + bg1;
;                     f32x4 u0, u1;
; #pragma unroll
;                     for (int j = 0; j < 4; ++j) { u0[j] = a0[j] * __builtin_amdgcn_rcpf(1.f + __expf(-g0[j])); u1[j] = a1[j] * __builtin_amdgcn_rcpf(1.f + __expf(-g1[j])); }
;                     *(u32x4*)(O + (size_t)(row0 + ai * HALF + m * 16) * ldc + ucol) = pack8(u0, u1); }
.LBB0_733:
	v_lshl_add_u32 v216, s35, 8, v222
	v_ashrrev_i32_e32 v217, 31, v216
	v_or_b32_e32 v214, 16, v216
	v_or_b32_e32 v212, 32, v216
	v_or_b32_e32 v210, 48, v216
	v_add_u32_e32 v208, 0x80, v216
	v_lshl_add_u64 v[128:129], v[216:217], 3, s[88:89]
	v_ashrrev_i32_e32 v215, 31, v214
	v_ashrrev_i32_e32 v213, 31, v212
	v_ashrrev_i32_e32 v211, 31, v210
	v_ashrrev_i32_e32 v209, 31, v208
	v_add_u32_e32 v206, 0x90, v216
	v_add_u32_e32 v204, 0xa0, v216
	v_add_u32_e32 v202, 0xb0, v216
	v_lshl_add_u64 v[130:131], v[214:215], 3, s[88:89]
	v_lshl_add_u64 v[132:133], v[212:213], 3, s[88:89]
	v_lshl_add_u64 v[134:135], v[210:211], 3, s[88:89]
	global_load_dwordx2 v[200:201], v[128:129], off
	global_load_dwordx2 v[198:199], v[130:131], off
	global_load_dwordx2 v[196:197], v[132:133], off
	global_load_dwordx2 v[194:195], v[134:135], off
	v_lshl_add_u64 v[128:129], v[208:209], 3, s[88:89]
	v_ashrrev_i32_e32 v207, 31, v206
	v_ashrrev_i32_e32 v205, 31, v204
	v_ashrrev_i32_e32 v203, 31, v202
	v_lshl_add_u64 v[130:131], v[206:207], 3, s[88:89]
	v_lshl_add_u64 v[132:133], v[204:205], 3, s[88:89]
	v_lshl_add_u64 v[134:135], v[202:203], 3, s[88:89]
	global_load_dwordx2 v[192:193], v[128:129], off
	global_load_dwordx2 v[190:191], v[130:131], off
	global_load_dwordx2 v[188:189], v[132:133], off
	global_load_dwordx2 v[186:187], v[134:135], off
	v_lshl_or_b32 v164, s34, 8, v233
	s_cmp_lt_i32 s34, 4
	s_mov_b64 s[4:5], -1
	s_cbranch_scc0 .LBB0_736
	v_ashrrev_i32_e32 v129, 31, v164
	v_mov_b32_e32 v128, v164
	v_readlane_b32 s4, v254, 16
	v_lshlrev_b64 v[128:129], 2, v[128:129]
	v_readlane_b32 s5, v254, 17
	v_lshl_or_b32 v220, s34, 7, v233
	v_ashrrev_i32_e32 v221, 31, v220
	v_lshl_add_u64 v[140:141], s[4:5], 0, v[128:129]
	v_readlane_b32 s4, v253, 51
	v_readlane_b32 s5, v253, 52
	global_load_dwordx4 v[136:139], v[140:141], off offset:16
	global_load_dwordx4 v[148:151], v[140:141], off
	v_lshl_add_u64 v[156:157], s[4:5], 0, v[128:129]
	global_load_dwordx4 v[128:131], v[156:157], off offset:16
	global_load_dwordx4 v[144:147], v[156:157], off
	global_load_dwordx4 v[132:135], v[140:141], off offset:528
	global_load_dwordx4 v[152:155], v[140:141], off offset:512
	s_nop 0
	global_load_dwordx4 v[140:143], v[156:157], off offset:528
	s_nop 0
	global_load_dwordx4 v[156:159], v[156:157], off offset:512
	v_readlane_b32 s4, v252, 36
	v_readlane_b32 s5, v252, 37
	s_movk_i32 s15, 0x1400
	v_lshlrev_b64 v[220:221], 1, v[220:221]
	v_mov_b64_e32 v[218:219], s[4:5]
	v_mad_i64_i32 v[236:237], s[4:5], v216, s15, v[218:219]
	v_lshl_add_u64 v[236:237], v[236:237], 0, v[220:221]
	s_waitcnt vmcnt(0)
	s_mov_b32 s4, 0xbfb8aa3b
	v_pk_fma_f32 v[68:69], v[200:201], v[152:153], v[68:69] op_sel_hi:[0,1,1] neg_lo:[1,0,0] neg_hi:[1,0,0]
	v_pk_fma_f32 v[70:71], v[200:201], v[154:155], v[70:71] op_sel_hi:[0,1,1] neg_lo:[1,0,0] neg_hi:[1,0,0]
	v_pk_fma_f32 v[56:57], v[200:201], v[132:133], v[56:57] op_sel_hi:[0,1,1] neg_lo:[1,0,0] neg_hi:[1,0,0]
	v_pk_fma_f32 v[58:59], v[200:201], v[134:135], v[58:59] op_sel_hi:[0,1,1] neg_lo:[1,0,0] neg_hi:[1,0,0]
	v_pk_fma_f32 v[68:69], v[200:201], v[68:69], v[156:157] op_sel:[1,0,0]
	v_pk_fma_f32 v[70:71], v[200:201], v[70:71], v[158:159] op_sel:[1,0,0]
	v_pk_fma_f32 v[56:57], v[200:201], v[56:57], v[140:141] op_sel:[1,0,0]
	v_pk_fma_f32 v[58:59], v[200:201], v[58:59], v[142:143] op_sel:[1,0,0]
	v_pk_mul_f32 v[68:69], v[68:69], s[4:5] op_sel_hi:[1,0]
	v_pk_mul_f32 v[70:71], v[70:71], s[4:5] op_sel_hi:[1,0]
	v_pk_mul_f32 v[56:57], v[56:57], s[4:5] op_sel_hi:[1,0]
	v_pk_mul_f32 v[58:59], v[58:59], s[4:5] op_sel_hi:[1,0]
	v_exp_f32_e32 v68, v68
	v_exp_f32_e32 v69, v69
	v_exp_f32_e32 v70, v70
	v_exp_f32_e32 v71, v71
	v_exp_f32_e32 v56, v56
	v_exp_f32_e32 v57, v57
	v_exp_f32_e32 v58, v58
	v_exp_f32_e32 v59, v59
	v_pk_fma_f32 v[124:125], v[200:201], v[148:149], v[124:125] op_sel_hi:[0,1,1] neg_lo:[1,0,0] neg_hi:[1,0,0]
	v_pk_fma_f32 v[126:127], v[200:201], v[150:151], v[126:127] op_sel_hi:[0,1,1] neg_lo:[1,0,0] neg_hi:[1,0,0]
	v_pk_fma_f32 v[120:121], v[200:201], v[136:137], v[120:121] op_sel_hi:[0,1,1] neg_lo:[1,0,0] neg_hi:[1,0,0]
	v_pk_fma_f32 v[122:123], v[200:201], v[138:139], v[122:123] op_sel_hi:[0,1,1] neg_lo:[1,0,0] neg_hi:[1,0,0]
	v_add_f32_e32 v68, 1.0, v68
	v_add_f32_e32 v69, 1.0, v69
	v_add_f32_e32 v70, 1.0, v70
	v_add_f32_e32 v71, 1.0, v71
	v_add_f32_e32 v56, 1.0, v56
	v_add_f32_e32 v57, 1.0, v57
	v_add_f32_e32 v58, 1.0, v58
	v_add_f32_e32 v59, 1.0, v59
	v_rcp_f32_e32 v68, v68
	v_rcp_f32_e32 v69, v69
	v_rcp_f32_e32 v70, v70
	v_rcp_f32_e32 v71, v71
	v_rcp_f32_e32 v56, v56
	v_rcp_f32_e32 v57, v57
	v_rcp_f32_e32 v58, v58
	v_rcp_f32_e32 v59, v59
	v_pk_fma_f32 v[124:125], v[200:201], v[124:125], v[144:145] op_sel:[1,0,0]
	v_pk_fma_f32 v[126:127], v[200:201], v[126:127], v[146:147] op_sel:[1,0,0]
	v_pk_fma_f32 v[120:121], v[200:201], v[120:121], v[128:129] op_sel:[1,0,0]
	v_pk_fma_f32 v[122:123], v[200:201], v[122:123], v[130:131] op_sel:[1,0,0]
	v_pk_mul_f32 v[124:125], v[124:125], v[68:69]
	v_pk_mul_f32 v[126:127], v[126:127], v[70:71]
	v_pk_mul_f32 v[120:121], v[120:121], v[56:57]
	v_pk_mul_f32 v[122:123], v[122:123], v[58:59]
	v_cvt_pk_bf16_f32 v160, v124, v125
	v_cvt_pk_bf16_f32 v161, v126, v127
	v_cvt_pk_bf16_f32 v162, v120, v121
	v_cvt_pk_bf16_f32 v163, v122, v123
	global_store_dwordx4 v[236:237], v[160:163], off
	s_mov_b32 s4, 0xbfb8aa3b
	v_pk_fma_f32 v[52:53], v[198:199], v[152:153], v[52:53] op_sel_hi:[0,1,1] neg_lo:[1,0,0] neg_hi:[1,0,0]
	v_pk_fma_f32 v[54:55], v[198:199], v[154:155], v[54:55] op_sel_hi:[0,1,1] neg_lo:[1,0,0] neg_hi:[1,0,0]
	v_pk_fma_f32 v[48:49], v[198:199], v[132:133], v[48:49] op_sel_hi:[0,1,1] neg_lo:[1,0,0] neg_hi:[1,0,0]
; __device__ __forceinline__ u32x4 pack8(const f32x4 v0, const f32x4 v1) { u32x4 w; w.x = cvt_pk_bf16(v0[0], v0[1]); w.y = cvt_pk_bf16(v0[2], v0[3]); w.z = cvt_pk_bf16(v1[0], v1[1]); w.w = cvt_pk_bf16(v1[2], v1[3]); return w; }
;     __device__ __forceinline__ void operator()(const f32x4 (&acc)[2][2][4][2], const Unit& u, int wr, int wc, int fr, int fq) const {
;     ...
;             for (int ai = 0; ai < 2; ++ai)
; #pragma unroll
;                 for (int m = 0; m < 4; ++m) {
;                     const f32x4 a0 = (acc[ai][0][m][0] - sa0 * mu[ai][m]) * rs[ai][m] + ba0, a1 = (acc[ai][0][m][1] - sa1 * mu[ai][m]) * rs[ai][m] + ba1;
;                     const f32x4 g0 = (acc[ai][1][m][0] - sg0 * mu[ai][m]) * rs[ai][m] + bg0, g1 = (acc[ai][1][m][1] - sg1 * mu[ai][m]) * rs[ai][m] + bg1;
;                     f32x4 u0, u1;
; #pragma unroll
;                     for (int j = 0; j < 4; ++j) { u0[j] = a0[j] * __builtin_amdgcn_rcpf(1.f + __expf(-g0[j])); u1[j] = a1[j] * __builtin_amdgcn_rcpf(1.f + __expf(-g1[j])); }
;                     *(u32x4*)(O + (size_t)(row0 + ai * HALF + m * 16) * ldc + ucol) = pack8(u0, u1); }
	v_pk_fma_f32 v[50:51], v[198:199], v[134:135], v[50:51] op_sel_hi:[0,1,1] neg_lo:[1,0,0] neg_hi:[1,0,0]
	v_pk_fma_f32 v[52:53], v[198:199], v[52:53], v[156:157] op_sel:[1,0,0]
	v_pk_fma_f32 v[54:55], v[198:199], v[54:55], v[158:159] op_sel:[1,0,0]
	v_pk_fma_f32 v[48:49], v[198:199], v[48:49], v[140:141] op_sel:[1,0,0]
	v_pk_fma_f32 v[50:51], v[198:199], v[50:51], v[142:143] op_sel:[1,0,0]
	v_pk_mul_f32 v[52:53], v[52:53], s[4:5] op_sel_hi:[1,0]
	v_pk_mul_f32 v[54:55], v[54:55], s[4:5] op_sel_hi:[1,0]
	v_pk_mul_f32 v[48:49], v[48:49], s[4:5] op_sel_hi:[1,0]
	v_pk_mul_f32 v[50:51], v[50:51], s[4:5] op_sel_hi:[1,0]
	v_exp_f32_e32 v52, v52
	v_exp_f32_e32 v53, v53
	v_exp_f32_e32 v54, v54
	v_exp_f32_e32 v55, v55
	v_exp_f32_e32 v48, v48
	v_exp_f32_e32 v49, v49
	v_exp_f32_e32 v50, v50
	v_exp_f32_e32 v51, v51
	v_pk_fma_f32 v[116:117], v[198:199], v[148:149], v[116:117] op_sel_hi:[0,1,1] neg_lo:[1,0,0] neg_hi:[1,0,0]
	v_pk_fma_f32 v[118:119], v[198:199], v[150:151], v[118:119] op_sel_hi:[0,1,1] neg_lo:[1,0,0] neg_hi:[1,0,0]
	v_pk_fma_f32 v[112:113], v[198:199], v[136:137], v[112:113] op_sel_hi:[0,1,1] neg_lo:[1,0,0] neg_hi:[1,0,0]
	v_pk_fma_f32 v[114:115], v[198:199], v[138:139], v[114:115] op_sel_hi:[0,1,1] neg_lo:[1,0,0] neg_hi:[1,0,0]
	v_add_f32_e32 v52, 1.0, v52
	v_add_f32_e32 v53, 1.0, v53
	v_add_f32_e32 v54, 1.0, v54
	v_add_f32_e32 v55, 1.0, v55
	v_add_f32_e32 v48, 1.0, v48
	v_add_f32_e32 v49, 1.0, v49
	v_add_f32_e32 v50, 1.0, v50
	v_add_f32_e32 v51, 1.0, v51
	v_rcp_f32_e32 v52, v52
	v_rcp_f32_e32 v53, v53
	v_rcp_f32_e32 v54, v54
	v_rcp_f32_e32 v55, v55
	v_rcp_f32_e32 v48, v48
	v_rcp_f32_e32 v49, v49
	v_rcp_f32_e32 v50, v50
	v_rcp_f32_e32 v51, v51
	v_pk_fma_f32 v[116:117], v[198:199], v[116:117], v[144:145] op_sel:[1,0,0]
	v_pk_fma_f32 v[118:119], v[198:199], v[118:119], v[146:147] op_sel:[1,0,0]
	v_pk_fma_f32 v[112:113], v[198:199], v[112:113], v[128:129] op_sel:[1,0,0]
	v_pk_fma_f32 v[114:115], v[198:199], v[114:115], v[130:131] op_sel:[1,0,0]
	v_pk_mul_f32 v[116:117], v[116:117], v[52:53]
	v_pk_mul_f32 v[118:119], v[118:119], v[54:55]
	v_pk_mul_f32 v[112:113], v[112:113], v[48:49]
	v_pk_mul_f32 v[114:115], v[114:115], v[50:51]
	v_mad_i64_i32 v[236:237], s[4:5], v214, s15, v[218:219]
	v_lshl_add_u64 v[236:237], v[236:237], 0, v[220:221]
	v_cvt_pk_bf16_f32 v160, v116, v117
	v_cvt_pk_bf16_f32 v161, v118, v119
	v_cvt_pk_bf16_f32 v162, v112, v113
	v_cvt_pk_bf16_f32 v163, v114, v115
	global_store_dwordx4 v[236:237], v[160:163], off
	s_mov_b32 s4, 0xbfb8aa3b
	v_pk_fma_f32 v[44:45], v[196:197], v[152:153], v[44:45] op_sel_hi:[0,1,1] neg_lo:[1,0,0] neg_hi:[1,0,0]
	v_pk_fma_f32 v[46:47], v[196:197], v[154:155], v[46:47] op_sel_hi:[0,1,1] neg_lo:[1,0,0] neg_hi:[1,0,0]
	v_pk_fma_f32 v[40:41], v[196:197], v[132:133], v[40:41] op_sel_hi:[0,1,1] neg_lo:[1,0,0] neg_hi:[1,0,0]
	v_pk_fma_f32 v[42:43], v[196:197], v[134:135], v[42:43] op_sel_hi:[0,1,1] neg_lo:[1,0,0] neg_hi:[1,0,0]
	v_pk_fma_f32 v[44:45], v[196:197], v[44:45], v[156:157] op_sel:[1,0,0]
	v_pk_fma_f32 v[46:47], v[196:197], v[46:47], v[158:159] op_sel:[1,0,0]
	v_pk_fma_f32 v[40:41], v[196:197], v[40:41], v[140:141] op_sel:[1,0,0]
	v_pk_fma_f32 v[42:43], v[196:197], v[42:43], v[142:143] op_sel:[1,0,0]
	v_pk_mul_f32 v[44:45], v[44:45], s[4:5] op_sel_hi:[1,0]
	v_pk_mul_f32 v[46:47], v[46:47], s[4:5] op_sel_hi:[1,0]
	v_pk_mul_f32 v[40:41], v[40:41], s[4:5] op_sel_hi:[1,0]
	v_pk_mul_f32 v[42:43], v[42:43], s[4:5] op_sel_hi:[1,0]
	v_exp_f32_e32 v44, v44
	v_exp_f32_e32 v45, v45
	v_exp_f32_e32 v46, v46
	v_exp_f32_e32 v47, v47
	v_exp_f32_e32 v40, v40
	v_exp_f32_e32 v41, v41
	v_exp_f32_e32 v42, v42
	v_exp_f32_e32 v43, v43
	v_pk_fma_f32 v[108:109], v[196:197], v[148:149], v[108:109] op_sel_hi:[0,1,1] neg_lo:[1,0,0] neg_hi:[1,0,0]
	v_pk_fma_f32 v[110:111], v[196:197], v[150:151], v[110:111] op_sel_hi:[0,1,1] neg_lo:[1,0,0] neg_hi:[1,0,0]
	v_pk_fma_f32 v[104:105], v[196:197], v[136:137], v[104:105] op_sel_hi:[0,1,1] neg_lo:[1,0,0] neg_hi:[1,0,0]
	v_pk_fma_f32 v[106:107], v[196:197], v[138:139], v[106:107] op_sel_hi:[0,1,1] neg_lo:[1,0,0] neg_hi:[1,0,0]
	v_add_f32_e32 v44, 1.0, v44
	v_add_f32_e32 v45, 1.0, v45
	v_add_f32_e32 v46, 1.0, v46
	v_add_f32_e32 v47, 1.0, v47
	v_add_f32_e32 v40, 1.0, v40
	v_add_f32_e32 v41, 1.0, v41
	v_add_f32_e32 v42, 1.0, v42
	v_add_f32_e32 v43, 1.0, v43
	v_rcp_f32_e32 v44, v44
	v_rcp_f32_e32 v45, v45
	v_rcp_f32_e32 v46, v46
	v_rcp_f32_e32 v47, v47
	v_rcp_f32_e32 v40, v40
	v_rcp_f32_e32 v41, v41
	v_rcp_f32_e32 v42, v42
	v_rcp_f32_e32 v43, v43
	v_pk_fma_f32 v[108:109], v[196:197], v[108:109], v[144:145] op_sel:[1,0,0]
	v_pk_fma_f32 v[110:111], v[196:197], v[110:111], v[146:147] op_sel:[1,0,0]
	v_pk_fma_f32 v[104:105], v[196:197], v[104:105], v[128:129] op_sel:[1,0,0]
	v_pk_fma_f32 v[106:107], v[196:197], v[106:107], v[130:131] op_sel:[1,0,0]
	v_pk_mul_f32 v[108:109], v[108:109], v[44:45]
	v_pk_mul_f32 v[110:111], v[110:111], v[46:47]
	v_pk_mul_f32 v[104:105], v[104:105], v[40:41]
	v_pk_mul_f32 v[106:107], v[106:107], v[42:43]
	v_mad_i64_i32 v[236:237], s[4:5], v212, s15, v[218:219]
	v_lshl_add_u64 v[236:237], v[236:237], 0, v[220:221]
	v_cvt_pk_bf16_f32 v160, v108, v109
	v_cvt_pk_bf16_f32 v161, v110, v111
	v_cvt_pk_bf16_f32 v162, v104, v105
	v_cvt_pk_bf16_f32 v163, v106, v107
	global_store_dwordx4 v[236:237], v[160:163], off
	s_mov_b32 s4, 0xbfb8aa3b
	v_pk_fma_f32 v[36:37], v[194:195], v[152:153], v[36:37] op_sel_hi:[0,1,1] neg_lo:[1,0,0] neg_hi:[1,0,0]
	v_pk_fma_f32 v[38:39], v[194:195], v[154:155], v[38:39] op_sel_hi:[0,1,1] neg_lo:[1,0,0] neg_hi:[1,0,0]
	v_pk_fma_f32 v[32:33], v[194:195], v[132:133], v[32:33] op_sel_hi:[0,1,1] neg_lo:[1,0,0] neg_hi:[1,0,0]
; __device__ __forceinline__ u32x4 pack8(const f32x4 v0, const f32x4 v1) { u32x4 w; w.x = cvt_pk_bf16(v0[0], v0[1]); w.y = cvt_pk_bf16(v0[2], v0[3]); w.z = cvt_pk_bf16(v1[0], v1[1]); w.w = cvt_pk_bf16(v1[2], v1[3]); return w; }
;     __device__ __forceinline__ void operator()(const f32x4 (&acc)[2][2][4][2], const Unit& u, int wr, int wc, int fr, int fq) const {
;     ...
;             for (int ai = 0; ai < 2; ++ai)
; #pragma unroll
;                 for (int m = 0; m < 4; ++m) {
;                     const f32x4 a0 = (acc[ai][0][m][0] - sa0 * mu[ai][m]) * rs[ai][m] + ba0, a1 = (acc[ai][0][m][1] - sa1 * mu[ai][m]) * rs[ai][m] + ba1;
;                     const f32x4 g0 = (acc[ai][1][m][0] - sg0 * mu[ai][m]) * rs[ai][m] + bg0, g1 = (acc[ai][1][m][1] - sg1 * mu[ai][m]) * rs[ai][m] + bg1;
;                     f32x4 u0, u1;
; #pragma unroll
;                     for (int j = 0; j < 4; ++j) { u0[j] = a0[j] * __builtin_amdgcn_rcpf(1.f + __expf(-g0[j])); u1[j] = a1[j] * __builtin_amdgcn_rcpf(1.f + __expf(-g1[j])); }
;                     *(u32x4*)(O + (size_t)(row0 + ai * HALF + m * 16) * ldc + ucol) = pack8(u0, u1); }
	v_pk_fma_f32 v[34:35], v[194:195], v[134:135], v[34:35] op_sel_hi:[0,1,1] neg_lo:[1,0,0] neg_hi:[1,0,0]
	v_pk_fma_f32 v[36:37], v[194:195], v[36:37], v[156:157] op_sel:[1,0,0]
	v_pk_fma_f32 v[38:39], v[194:195], v[38:39], v[158:159] op_sel:[1,0,0]
	v_pk_fma_f32 v[32:33], v[194:195], v[32:33], v[140:141] op_sel:[1,0,0]
	v_pk_fma_f32 v[34:35], v[194:195], v[34:35], v[142:143] op_sel:[1,0,0]
	v_pk_mul_f32 v[36:37], v[36:37], s[4:5] op_sel_hi:[1,0]
	v_pk_mul_f32 v[38:39], v[38:39], s[4:5] op_sel_hi:[1,0]
	v_pk_mul_f32 v[32:33], v[32:33], s[4:5] op_sel_hi:[1,0]
	v_pk_mul_f32 v[34:35], v[34:35], s[4:5] op_sel_hi:[1,0]
	v_exp_f32_e32 v36, v36
	v_exp_f32_e32 v37, v37
	v_exp_f32_e32 v38, v38
	v_exp_f32_e32 v39, v39
	v_exp_f32_e32 v32, v32
	v_exp_f32_e32 v33, v33
	v_exp_f32_e32 v34, v34
	v_exp_f32_e32 v35, v35
	v_pk_fma_f32 v[100:101], v[194:195], v[148:149], v[100:101] op_sel_hi:[0,1,1] neg_lo:[1,0,0] neg_hi:[1,0,0]
	v_pk_fma_f32 v[102:103], v[194:195], v[150:151], v[102:103] op_sel_hi:[0,1,1] neg_lo:[1,0,0] neg_hi:[1,0,0]
	v_pk_fma_f32 v[96:97], v[194:195], v[136:137], v[96:97] op_sel_hi:[0,1,1] neg_lo:[1,0,0] neg_hi:[1,0,0]
	v_pk_fma_f32 v[98:99], v[194:195], v[138:139], v[98:99] op_sel_hi:[0,1,1] neg_lo:[1,0,0] neg_hi:[1,0,0]
	v_add_f32_e32 v36, 1.0, v36
	v_add_f32_e32 v37, 1.0, v37
	v_add_f32_e32 v38, 1.0, v38
	v_add_f32_e32 v39, 1.0, v39
	v_add_f32_e32 v32, 1.0, v32
	v_add_f32_e32 v33, 1.0, v33
	v_add_f32_e32 v34, 1.0, v34
	v_add_f32_e32 v35, 1.0, v35
	v_rcp_f32_e32 v36, v36
	v_rcp_f32_e32 v37, v37
	v_rcp_f32_e32 v38, v38
	v_rcp_f32_e32 v39, v39
	v_rcp_f32_e32 v32, v32
	v_rcp_f32_e32 v33, v33
	v_rcp_f32_e32 v34, v34
	v_rcp_f32_e32 v35, v35
	v_pk_fma_f32 v[100:101], v[194:195], v[100:101], v[144:145] op_sel:[1,0,0]
	v_pk_fma_f32 v[102:103], v[194:195], v[102:103], v[146:147] op_sel:[1,0,0]
	v_pk_fma_f32 v[96:97], v[194:195], v[96:97], v[128:129] op_sel:[1,0,0]
	v_pk_fma_f32 v[98:99], v[194:195], v[98:99], v[130:131] op_sel:[1,0,0]
	v_pk_mul_f32 v[100:101], v[100:101], v[36:37]
	v_pk_mul_f32 v[102:103], v[102:103], v[38:39]
	v_pk_mul_f32 v[96:97], v[96:97], v[32:33]
	v_pk_mul_f32 v[98:99], v[98:99], v[34:35]
	v_mad_i64_i32 v[236:237], s[4:5], v210, s15, v[218:219]
	v_lshl_add_u64 v[236:237], v[236:237], 0, v[220:221]
	v_cvt_pk_bf16_f32 v160, v100, v101
	v_cvt_pk_bf16_f32 v161, v102, v103
	v_cvt_pk_bf16_f32 v162, v96, v97
	v_cvt_pk_bf16_f32 v163, v98, v99
	global_store_dwordx4 v[236:237], v[160:163], off
	s_mov_b32 s4, 0xbfb8aa3b
	v_pk_fma_f32 v[28:29], v[192:193], v[152:153], v[28:29] op_sel_hi:[0,1,1] neg_lo:[1,0,0] neg_hi:[1,0,0]
	v_pk_fma_f32 v[30:31], v[192:193], v[154:155], v[30:31] op_sel_hi:[0,1,1] neg_lo:[1,0,0] neg_hi:[1,0,0]
	v_pk_fma_f32 v[24:25], v[192:193], v[132:133], v[24:25] op_sel_hi:[0,1,1] neg_lo:[1,0,0] neg_hi:[1,0,0]
	v_pk_fma_f32 v[26:27], v[192:193], v[134:135], v[26:27] op_sel_hi:[0,1,1] neg_lo:[1,0,0] neg_hi:[1,0,0]
	v_pk_fma_f32 v[28:29], v[192:193], v[28:29], v[156:157] op_sel:[1,0,0]
	v_pk_fma_f32 v[30:31], v[192:193], v[30:31], v[158:159] op_sel:[1,0,0]
	v_pk_fma_f32 v[24:25], v[192:193], v[24:25], v[140:141] op_sel:[1,0,0]
	v_pk_fma_f32 v[26:27], v[192:193], v[26:27], v[142:143] op_sel:[1,0,0]
	v_pk_mul_f32 v[28:29], v[28:29], s[4:5] op_sel_hi:[1,0]
	v_pk_mul_f32 v[30:31], v[30:31], s[4:5] op_sel_hi:[1,0]
	v_pk_mul_f32 v[24:25], v[24:25], s[4:5] op_sel_hi:[1,0]
	v_pk_mul_f32 v[26:27], v[26:27], s[4:5] op_sel_hi:[1,0]
	v_exp_f32_e32 v28, v28
	v_exp_f32_e32 v29, v29
	v_exp_f32_e32 v30, v30
	v_exp_f32_e32 v31, v31
	v_exp_f32_e32 v24, v24
	v_exp_f32_e32 v25, v25
	v_exp_f32_e32 v26, v26
	v_exp_f32_e32 v27, v27
	v_pk_fma_f32 v[92:93], v[192:193], v[148:149], v[92:93] op_sel_hi:[0,1,1] neg_lo:[1,0,0] neg_hi:[1,0,0]
	v_pk_fma_f32 v[94:95], v[192:193], v[150:151], v[94:95] op_sel_hi:[0,1,1] neg_lo:[1,0,0] neg_hi:[1,0,0]
	v_pk_fma_f32 v[88:89], v[192:193], v[136:137], v[88:89] op_sel_hi:[0,1,1] neg_lo:[1,0,0] neg_hi:[1,0,0]
	v_pk_fma_f32 v[90:91], v[192:193], v[138:139], v[90:91] op_sel_hi:[0,1,1] neg_lo:[1,0,0] neg_hi:[1,0,0]
	v_add_f32_e32 v28, 1.0, v28
	v_add_f32_e32 v29, 1.0, v29
	v_add_f32_e32 v30, 1.0, v30
	v_add_f32_e32 v31, 1.0, v31
	v_add_f32_e32 v24, 1.0, v24
	v_add_f32_e32 v25, 1.0, v25
	v_add_f32_e32 v26, 1.0, v26
	v_add_f32_e32 v27, 1.0, v27
	v_rcp_f32_e32 v28, v28
	v_rcp_f32_e32 v29, v29
	v_rcp_f32_e32 v30, v30
	v_rcp_f32_e32 v31, v31
	v_rcp_f32_e32 v24, v24
	v_rcp_f32_e32 v25, v25
	v_rcp_f32_e32 v26, v26
	v_rcp_f32_e32 v27, v27
	v_pk_fma_f32 v[92:93], v[192:193], v[92:93], v[144:145] op_sel:[1,0,0]
	v_pk_fma_f32 v[94:95], v[192:193], v[94:95], v[146:147] op_sel:[1,0,0]
	v_pk_fma_f32 v[88:89], v[192:193], v[88:89], v[128:129] op_sel:[1,0,0]
	v_pk_fma_f32 v[90:91], v[192:193], v[90:91], v[130:131] op_sel:[1,0,0]
	v_pk_mul_f32 v[92:93], v[92:93], v[28:29]
	v_pk_mul_f32 v[94:95], v[94:95], v[30:31]
	v_pk_mul_f32 v[88:89], v[88:89], v[24:25]
	v_pk_mul_f32 v[90:91], v[90:91], v[26:27]
	v_mad_i64_i32 v[236:237], s[4:5], v208, s15, v[218:219]
	v_lshl_add_u64 v[236:237], v[236:237], 0, v[220:221]
	v_cvt_pk_bf16_f32 v160, v92, v93
	v_cvt_pk_bf16_f32 v161, v94, v95
	v_cvt_pk_bf16_f32 v162, v88, v89
	v_cvt_pk_bf16_f32 v163, v90, v91
	global_store_dwordx4 v[236:237], v[160:163], off
	s_mov_b32 s4, 0xbfb8aa3b
	v_pk_fma_f32 v[20:21], v[190:191], v[152:153], v[20:21] op_sel_hi:[0,1,1] neg_lo:[1,0,0] neg_hi:[1,0,0]
	v_pk_fma_f32 v[22:23], v[190:191], v[154:155], v[22:23] op_sel_hi:[0,1,1] neg_lo:[1,0,0] neg_hi:[1,0,0]
	v_pk_fma_f32 v[16:17], v[190:191], v[132:133], v[16:17] op_sel_hi:[0,1,1] neg_lo:[1,0,0] neg_hi:[1,0,0]
	v_pk_fma_f32 v[18:19], v[190:191], v[134:135], v[18:19] op_sel_hi:[0,1,1] neg_lo:[1,0,0] neg_hi:[1,0,0]
; __device__ __forceinline__ u32x4 pack8(const f32x4 v0, const f32x4 v1) { u32x4 w; w.x = cvt_pk_bf16(v0[0], v0[1]); w.y = cvt_pk_bf16(v0[2], v0[3]); w.z = cvt_pk_bf16(v1[0], v1[1]); w.w = cvt_pk_bf16(v1[2], v1[3]); return w; }
;     __device__ __forceinline__ void operator()(const f32x4 (&acc)[2][2][4][2], const Unit& u, int wr, int wc, int fr, int fq) const {
;     ...
;             for (int ai = 0; ai < 2; ++ai)
; #pragma unroll
;                 for (int m = 0; m < 4; ++m) {
;                     const f32x4 a0 = (acc[ai][0][m][0] - sa0 * mu[ai][m]) * rs[ai][m] + ba0, a1 = (acc[ai][0][m][1] - sa1 * mu[ai][m]) * rs[ai][m] + ba1;
;                     const f32x4 g0 = (acc[ai][1][m][0] - sg0 * mu[ai][m]) * rs[ai][m] + bg0, g1 = (acc[ai][1][m][1] - sg1 * mu[ai][m]) * rs[ai][m] + bg1;
;                     f32x4 u0, u1;
; #pragma unroll
;                     for (int j = 0; j < 4; ++j) { u0[j] = a0[j] * __builtin_amdgcn_rcpf(1.f + __expf(-g0[j])); u1[j] = a1[j] * __builtin_amdgcn_rcpf(1.f + __expf(-g1[j])); }
;                     *(u32x4*)(O + (size_t)(row0 + ai * HALF + m * 16) * ldc + ucol) = pack8(u0, u1); }
	v_pk_fma_f32 v[20:21], v[190:191], v[20:21], v[156:157] op_sel:[1,0,0]
	v_pk_fma_f32 v[22:23], v[190:191], v[22:23], v[158:159] op_sel:[1,0,0]
	v_pk_fma_f32 v[16:17], v[190:191], v[16:17], v[140:141] op_sel:[1,0,0]
	v_pk_fma_f32 v[18:19], v[190:191], v[18:19], v[142:143] op_sel:[1,0,0]
	v_pk_mul_f32 v[20:21], v[20:21], s[4:5] op_sel_hi:[1,0]
	v_pk_mul_f32 v[22:23], v[22:23], s[4:5] op_sel_hi:[1,0]
	v_pk_mul_f32 v[16:17], v[16:17], s[4:5] op_sel_hi:[1,0]
	v_pk_mul_f32 v[18:19], v[18:19], s[4:5] op_sel_hi:[1,0]
	v_exp_f32_e32 v20, v20
	v_exp_f32_e32 v21, v21
	v_exp_f32_e32 v22, v22
	v_exp_f32_e32 v23, v23
	v_exp_f32_e32 v16, v16
	v_exp_f32_e32 v17, v17
	v_exp_f32_e32 v18, v18
	v_exp_f32_e32 v19, v19
	v_pk_fma_f32 v[84:85], v[190:191], v[148:149], v[84:85] op_sel_hi:[0,1,1] neg_lo:[1,0,0] neg_hi:[1,0,0]
	v_pk_fma_f32 v[86:87], v[190:191], v[150:151], v[86:87] op_sel_hi:[0,1,1] neg_lo:[1,0,0] neg_hi:[1,0,0]
	v_pk_fma_f32 v[80:81], v[190:191], v[136:137], v[80:81] op_sel_hi:[0,1,1] neg_lo:[1,0,0] neg_hi:[1,0,0]
	v_pk_fma_f32 v[82:83], v[190:191], v[138:139], v[82:83] op_sel_hi:[0,1,1] neg_lo:[1,0,0] neg_hi:[1,0,0]
	v_add_f32_e32 v20, 1.0, v20
	v_add_f32_e32 v21, 1.0, v21
	v_add_f32_e32 v22, 1.0, v22
	v_add_f32_e32 v23, 1.0, v23
	v_add_f32_e32 v16, 1.0, v16
	v_add_f32_e32 v17, 1.0, v17
	v_add_f32_e32 v18, 1.0, v18
	v_add_f32_e32 v19, 1.0, v19
	v_rcp_f32_e32 v20, v20
	v_rcp_f32_e32 v21, v21
	v_rcp_f32_e32 v22, v22
	v_rcp_f32_e32 v23, v23
	v_rcp_f32_e32 v16, v16
	v_rcp_f32_e32 v17, v17
	v_rcp_f32_e32 v18, v18
	v_rcp_f32_e32 v19, v19
	v_pk_fma_f32 v[84:85], v[190:191], v[84:85], v[144:145] op_sel:[1,0,0]
	v_pk_fma_f32 v[86:87], v[190:191], v[86:87], v[146:147] op_sel:[1,0,0]
	v_pk_fma_f32 v[80:81], v[190:191], v[80:81], v[128:129] op_sel:[1,0,0]
	v_pk_fma_f32 v[82:83], v[190:191], v[82:83], v[130:131] op_sel:[1,0,0]
	v_pk_mul_f32 v[84:85], v[84:85], v[20:21]
	v_pk_mul_f32 v[86:87], v[86:87], v[22:23]
	v_pk_mul_f32 v[80:81], v[80:81], v[16:17]
	v_pk_mul_f32 v[82:83], v[82:83], v[18:19]
	v_mad_i64_i32 v[236:237], s[4:5], v206, s15, v[218:219]
	v_lshl_add_u64 v[236:237], v[236:237], 0, v[220:221]
	v_cvt_pk_bf16_f32 v160, v84, v85
	v_cvt_pk_bf16_f32 v161, v86, v87
	v_cvt_pk_bf16_f32 v162, v80, v81
	v_cvt_pk_bf16_f32 v163, v82, v83
	global_store_dwordx4 v[236:237], v[160:163], off
	s_mov_b32 s4, 0xbfb8aa3b
	v_pk_fma_f32 v[12:13], v[188:189], v[152:153], v[12:13] op_sel_hi:[0,1,1] neg_lo:[1,0,0] neg_hi:[1,0,0]
	v_pk_fma_f32 v[14:15], v[188:189], v[154:155], v[14:15] op_sel_hi:[0,1,1] neg_lo:[1,0,0] neg_hi:[1,0,0]
	v_pk_fma_f32 v[8:9], v[188:189], v[132:133], v[8:9] op_sel_hi:[0,1,1] neg_lo:[1,0,0] neg_hi:[1,0,0]
	v_pk_fma_f32 v[10:11], v[188:189], v[134:135], v[10:11] op_sel_hi:[0,1,1] neg_lo:[1,0,0] neg_hi:[1,0,0]
	v_pk_fma_f32 v[12:13], v[188:189], v[12:13], v[156:157] op_sel:[1,0,0]
	v_pk_fma_f32 v[14:15], v[188:189], v[14:15], v[158:159] op_sel:[1,0,0]
	v_pk_fma_f32 v[8:9], v[188:189], v[8:9], v[140:141] op_sel:[1,0,0]
	v_pk_fma_f32 v[10:11], v[188:189], v[10:11], v[142:143] op_sel:[1,0,0]
	v_pk_mul_f32 v[12:13], v[12:13], s[4:5] op_sel_hi:[1,0]
	v_pk_mul_f32 v[14:15], v[14:15], s[4:5] op_sel_hi:[1,0]
	v_pk_mul_f32 v[8:9], v[8:9], s[4:5] op_sel_hi:[1,0]
	v_pk_mul_f32 v[10:11], v[10:11], s[4:5] op_sel_hi:[1,0]
	v_exp_f32_e32 v12, v12
	v_exp_f32_e32 v13, v13
	v_exp_f32_e32 v14, v14
	v_exp_f32_e32 v15, v15
	v_exp_f32_e32 v8, v8
	v_exp_f32_e32 v9, v9
	v_exp_f32_e32 v10, v10
	v_exp_f32_e32 v11, v11
	v_pk_fma_f32 v[76:77], v[188:189], v[148:149], v[76:77] op_sel_hi:[0,1,1] neg_lo:[1,0,0] neg_hi:[1,0,0]
	v_pk_fma_f32 v[78:79], v[188:189], v[150:151], v[78:79] op_sel_hi:[0,1,1] neg_lo:[1,0,0] neg_hi:[1,0,0]
	v_pk_fma_f32 v[72:73], v[188:189], v[136:137], v[72:73] op_sel_hi:[0,1,1] neg_lo:[1,0,0] neg_hi:[1,0,0]
	v_pk_fma_f32 v[74:75], v[188:189], v[138:139], v[74:75] op_sel_hi:[0,1,1] neg_lo:[1,0,0] neg_hi:[1,0,0]
; __device__ __forceinline__ u32x4 pack8(const f32x4 v0, const f32x4 v1) { u32x4 w; w.x = cvt_pk_bf16(v0[0], v0[1]); w.y = cvt_pk_bf16(v0[2], v0[3]); w.z = cvt_pk_bf16(v1[0], v1[1]); w.w = cvt_pk_bf16(v1[2], v1[3]); return w; }
;     __device__ __forceinline__ void operator()(const f32x4 (&acc)[2][2][4][2], const Unit& u, int wr, int wc, int fr, int fq) const {
;     ...
;             for (int ai = 0; ai < 2; ++ai)
; #pragma unroll
;                 for (int m = 0; m < 4; ++m) {
;                     const f32x4 a0 = (acc[ai][0][m][0] - sa0 * mu[ai][m]) * rs[ai][m] + ba0, a1 = (acc[ai][0][m][1] - sa1 * mu[ai][m]) * rs[ai][m] + ba1;
;                     const f32x4 g0 = (acc[ai][1][m][0] - sg0 * mu[ai][m]) * rs[ai][m] + bg0, g1 = (acc[ai][1][m][1] - sg1 * mu[ai][m]) * rs[ai][m] + bg1;
;                     f32x4 u0, u1;
; #pragma unroll
;                     for (int j = 0; j < 4; ++j) { u0[j] = a0[j] * __builtin_amdgcn_rcpf(1.f + __expf(-g0[j])); u1[j] = a1[j] * __builtin_amdgcn_rcpf(1.f + __expf(-g1[j])); }
;                     *(u32x4*)(O + (size_t)(row0 + ai * HALF + m * 16) * ldc + ucol) = pack8(u0, u1); }
	v_add_f32_e32 v12, 1.0, v12
	v_add_f32_e32 v13, 1.0, v13
	v_add_f32_e32 v14, 1.0, v14
	v_add_f32_e32 v15, 1.0, v15
	v_add_f32_e32 v8, 1.0, v8
	v_add_f32_e32 v9, 1.0, v9
	v_add_f32_e32 v10, 1.0, v10
	v_add_f32_e32 v11, 1.0, v11
	v_rcp_f32_e32 v12, v12
	v_rcp_f32_e32 v13, v13
	v_rcp_f32_e32 v14, v14
	v_rcp_f32_e32 v15, v15
	v_rcp_f32_e32 v8, v8
	v_rcp_f32_e32 v9, v9
	v_rcp_f32_e32 v10, v10
	v_rcp_f32_e32 v11, v11
	v_pk_fma_f32 v[76:77], v[188:189], v[76:77], v[144:145] op_sel:[1,0,0]
	v_pk_fma_f32 v[78:79], v[188:189], v[78:79], v[146:147] op_sel:[1,0,0]
	v_pk_fma_f32 v[72:73], v[188:189], v[72:73], v[128:129] op_sel:[1,0,0]
	v_pk_fma_f32 v[74:75], v[188:189], v[74:75], v[130:131] op_sel:[1,0,0]
	v_pk_mul_f32 v[76:77], v[76:77], v[12:13]
	v_pk_mul_f32 v[78:79], v[78:79], v[14:15]
	v_pk_mul_f32 v[72:73], v[72:73], v[8:9]
	v_pk_mul_f32 v[74:75], v[74:75], v[10:11]
	v_mad_i64_i32 v[236:237], s[4:5], v204, s15, v[218:219]
	v_lshl_add_u64 v[236:237], v[236:237], 0, v[220:221]
	v_cvt_pk_bf16_f32 v160, v76, v77
	v_cvt_pk_bf16_f32 v161, v78, v79
	v_cvt_pk_bf16_f32 v162, v72, v73
	v_cvt_pk_bf16_f32 v163, v74, v75
	global_store_dwordx4 v[236:237], v[160:163], off
	s_mov_b32 s4, 0xbfb8aa3b
	v_pk_fma_f32 v[4:5], v[186:187], v[152:153], v[4:5] op_sel_hi:[0,1,1] neg_lo:[1,0,0] neg_hi:[1,0,0]
	v_pk_fma_f32 v[6:7], v[186:187], v[154:155], v[6:7] op_sel_hi:[0,1,1] neg_lo:[1,0,0] neg_hi:[1,0,0]
	v_pk_fma_f32 v[0:1], v[186:187], v[132:133], v[0:1] op_sel_hi:[0,1,1] neg_lo:[1,0,0] neg_hi:[1,0,0]
	v_pk_fma_f32 v[2:3], v[186:187], v[134:135], v[2:3] op_sel_hi:[0,1,1] neg_lo:[1,0,0] neg_hi:[1,0,0]
	v_pk_fma_f32 v[4:5], v[186:187], v[4:5], v[156:157] op_sel:[1,0,0]
	v_pk_fma_f32 v[6:7], v[186:187], v[6:7], v[158:159] op_sel:[1,0,0]
	v_pk_fma_f32 v[0:1], v[186:187], v[0:1], v[140:141] op_sel:[1,0,0]
	v_pk_fma_f32 v[2:3], v[186:187], v[2:3], v[142:143] op_sel:[1,0,0]
	v_pk_mul_f32 v[4:5], v[4:5], s[4:5] op_sel_hi:[1,0]
	v_pk_mul_f32 v[6:7], v[6:7], s[4:5] op_sel_hi:[1,0]
	v_pk_mul_f32 v[0:1], v[0:1], s[4:5] op_sel_hi:[1,0]
	v_pk_mul_f32 v[2:3], v[2:3], s[4:5] op_sel_hi:[1,0]
	v_exp_f32_e32 v4, v4
	v_exp_f32_e32 v5, v5
	v_exp_f32_e32 v6, v6
	v_exp_f32_e32 v7, v7
	v_exp_f32_e32 v0, v0
	v_exp_f32_e32 v1, v1
	v_exp_f32_e32 v2, v2
	v_exp_f32_e32 v3, v3
	v_pk_fma_f32 v[64:65], v[186:187], v[148:149], v[64:65] op_sel_hi:[0,1,1] neg_lo:[1,0,0] neg_hi:[1,0,0]
	v_pk_fma_f32 v[66:67], v[186:187], v[150:151], v[66:67] op_sel_hi:[0,1,1] neg_lo:[1,0,0] neg_hi:[1,0,0]
	v_pk_fma_f32 v[60:61], v[186:187], v[136:137], v[60:61] op_sel_hi:[0,1,1] neg_lo:[1,0,0] neg_hi:[1,0,0]
	v_pk_fma_f32 v[62:63], v[186:187], v[138:139], v[62:63] op_sel_hi:[0,1,1] neg_lo:[1,0,0] neg_hi:[1,0,0]
	v_add_f32_e32 v4, 1.0, v4
	v_add_f32_e32 v5, 1.0, v5
	v_add_f32_e32 v6, 1.0, v6
	v_add_f32_e32 v7, 1.0, v7
	v_add_f32_e32 v0, 1.0, v0
	v_add_f32_e32 v1, 1.0, v1
	v_add_f32_e32 v2, 1.0, v2
	v_add_f32_e32 v3, 1.0, v3
	v_rcp_f32_e32 v4, v4
	v_rcp_f32_e32 v5, v5
	v_rcp_f32_e32 v6, v6
	v_rcp_f32_e32 v7, v7
	v_rcp_f32_e32 v0, v0
	v_rcp_f32_e32 v1, v1
	v_rcp_f32_e32 v2, v2
	v_rcp_f32_e32 v3, v3
	v_pk_fma_f32 v[64:65], v[186:187], v[64:65], v[144:145] op_sel:[1,0,0]
	v_pk_fma_f32 v[66:67], v[186:187], v[66:67], v[146:147] op_sel:[1,0,0]
	v_pk_fma_f32 v[60:61], v[186:187], v[60:61], v[128:129] op_sel:[1,0,0]
	v_pk_fma_f32 v[62:63], v[186:187], v[62:63], v[130:131] op_sel:[1,0,0]
	v_pk_mul_f32 v[64:65], v[64:65], v[4:5]
	v_pk_mul_f32 v[66:67], v[66:67], v[6:7]
	v_pk_mul_f32 v[60:61], v[60:61], v[0:1]
	v_pk_mul_f32 v[62:63], v[62:63], v[2:3]
	v_mad_i64_i32 v[132:133], s[4:5], v202, s15, v[218:219]
	v_lshl_add_u64 v[132:133], v[132:133], 0, v[220:221]
	v_cvt_pk_bf16_f32 v128, v64, v65
	v_cvt_pk_bf16_f32 v129, v66, v67
	v_cvt_pk_bf16_f32 v130, v60, v61
	v_cvt_pk_bf16_f32 v131, v62, v63
	global_store_dwordx4 v[132:133], v[128:131], off
	s_cbranch_execz .LBB0_737
